# v12_scanjoin
# speedup vs baseline: 1.0481x; 1.0021x over previous
; #define LAS __attribute__((address_space(3)))
; __device__ __forceinline__ void phase_convert_late(const Params& p, LAS float* scr, int cw, int NCW, int lane) {
;     ...
;     for (int it = cw; it < I1 + I2 + I3 + I4 + I5 + I6; it += NCW) {
;         int r = it;
;         if (r < I6) { const int nb = r % 344, kb = r / 344; const int n0 = nb * 64; const int nn = n0 < FF ? n0 : n0 - FF; const int r0 = (nn >> 7) * 256 + (n0 < FF ? 0 : 128) + (nn & 127);
; __global__ void __launch_bounds__(NTHR, 2) mega_fwd(Params p) {
;     ...
;         if (wave >= 2) {
;             const int cw = vcu * 6 + (wave - 2), NCW = G * 6;
;             phase_pool((const bf16_t*)(ws + WS_SB), (bf16_t*)(ws + WS_SC + (size_t)MT * DSS * 2), cw, NCW, lane);
;             phase_convert_late(p, (LAS float*)(lds + 51200 + (wave - 2) * 16896), cw, NCW, lane);
;         } else phase_scan(p, lds, wave, lane, G);
.LBB0_296:
	v_readlane_b32 s1, v255, 3
	v_readlane_b32 s0, v255, 0
	s_lshl_b32 s35, s77, 1
	s_movk_i32 s98, 0x7aff
	s_add_i32 s35, s35, s1
	s_lshl_b32 s40, s0, 1
	s_addk_i32 s35, 0x7100
	s_mul_i32 s0, s1, 0x6400
	s_add_i32 s0, s0, 0xffff3800
	s_cmp_gt_i32 s35, s98
	s_cbranch_scc1 .LBB0_334
	s_branch .Lconv_entry2
.LBB0_297:
	s_andn2_b64 vcc, exec, s[0:1]
	s_cbranch_vccnz .LBB0_334
	s_movk_i32 s98, 0x70ff
	v_readlane_b32 s1, v255, 3
	s_mul_i32 s0, s77, 6
	s_add_i32 s3, s1, -2
	s_add_i32 s35, s0, s3
	v_readlane_b32 s0, v255, 0
	s_cmpk_gt_i32 s35, 0x7ff
	s_mul_i32 s40, s0, 6
	v_readlane_b32 s1, v255, 1
	s_cbranch_scc1 .LBB0_311
	s_add_u32 s8, s58, 0x2d114000
	s_addc_u32 s9, s59, 0
	v_and_b32_e32 v0, 63, v254
	s_lshl_b32 s4, s77, 1
	v_readlane_b32 s5, v255, 3
	v_lshlrev_b32_e32 v8, 3, v0
	v_mov_b32_e32 v1, 0
	v_lshlrev_b32_e32 v0, 4, v0
	s_add_i32 s4, s4, s5
	v_readlane_b32 s10, v255, 0
	v_lshl_add_u64 v[6:7], s[58:59], 0, v[0:1]
	s_add_i32 s61, s4, 2
	s_mov_b64 s[4:5], 0x2d115000
	v_readlane_b32 s11, v255, 1
	s_mov_b64 s[0:1], 0x1f115000
	v_lshl_add_u64 v[4:5], v[6:7], 0, s[4:5]
	s_mov_b64 s[4:5], 0x1f11b000
	s_lshl_b32 s33, s35, 2
	s_mul_i32 s41, s10, 24
	v_lshl_add_u64 v[2:3], v[6:7], 0, s[0:1]
	s_lshl_b32 s62, s10, 1
	v_lshl_add_u64 v[6:7], v[6:7], 0, s[4:5]
	s_mov_b32 s5, 0
	s_mov_b64 s[10:11], 0x6000
	v_lshlrev_b32_e32 v0, 1, v8
	s_mov_b64 s[14:15], 0x1000
	v_mov_b32_e32 v30, 0x6000
	s_mov_b32 s63, s35
	s_branch .LBB0_301

; #define LAS __attribute__((address_space(3)))
; __device__ __forceinline__ void transpose_item(const float* W, int N, bf16_t* WT, int nkt, int k0, int n0, int r0, int kbd, LAS float* scr, int lane) {
;     const size_t dst_off = ((size_t)(r0 >> 8) * nkt + kbd) * 16384 + (size_t)(r0 & 255) * 64;
;     const int l15 = lane & 15, lq = lane >> 4;
;     f32x4 v[16];
; #pragma unroll
;     for (int i = 0; i < 16; ++i) v[i] = *(const f32x4*)(W + (size_t)(k0 + 4 * i + lq) * N + n0 + 4 * l15);
; #pragma unroll
;     for (int i = 0; i < 16; ++i) { LAS float* d = scr + (4 * i + lq) * 65 + 4 * l15; d[0] = v[i][0]; d[1] = v[i][1]; d[2] = v[i][2]; d[3] = v[i][3]; }
;     LDS_WAIT();
;     const int c = lane & 7;
; #pragma unroll
; __device__ __forceinline__ void phase_convert_late(const Params& p, LAS float* scr, int cw, int NCW, int lane) {
;     unsigned char* ws = p.ws;
;     constexpr int I1 = 32 * 32, I2 = 4 * 8 * 8, I3 = 32 * 64, I4 = 32 * 64, I5 = 64 * 64, I6 = 64 * 344;
;     for (int it = cw; it < I1 + I2 + I3 + I4 + I5 + I6; it += NCW) {
;         int r = it;
;         if (r < I6) { const int nb = r % 344, kb = r / 344; const int n0 = nb * 64; const int nn = n0 < FF ? n0 : n0 - FF; const int r0 = (nn >> 7) * 256 + (n0 < FF ? 0 : 128) + (nn & 127);
;             transpose_item(p.in[21], FF2, (bf16_t*)(ws + WS_W_UP), 64, kb * 64, n0, r0, kb, scr, lane); continue; } r -= I6;
;         if (r < I1) { const int nb = r % 32, kb = r / 32; transpose_item(p.in[11], 2048, (bf16_t*)(ws + WS_W_GLU), 32, kb * 64, nb * 64, nb * 64, kb, scr, lane); continue; } r -= I1;
;         if (r < I2) { const int g = r >> 6, q = r & 63, nb = q & 7, kb = q >> 3; transpose_item(p.in[13] + (size_t)g * 512 * 512, 512, (bf16_t*)(ws + WS_W_POOL), 32, kb * 64, nb * 64, nb * 64, g * 8 + kb, scr, lane); continue; } r -= I2;
;         if (r < I3) { const int nb = r % 64, kb = r / 64; transpose_item(p.in[16], 4096, (bf16_t*)(ws + WS_W_BS), 32, kb * 64, nb * 64, nb * 64, kb, scr, lane); continue; } r -= I3;
;         if (r < I4) { const int nb = r % 64, kb = r / 64; transpose_item(p.in[17], 4096, (bf16_t*)(ws + WS_W_BP), 32, kb * 64, nb * 64, nb * 64, kb, scr, lane); continue; } r -= I4;
;         { const int nb = r % 64, kb = r / 64; transpose_item(p.in[18], 4096, (bf16_t*)(ws + WS_W_OUT), 64, kb * 64, nb * 64, nb * 64, kb, scr, lane); }
;     }
.LBB0_311:
	s_cmp_gt_i32 s35, s98
	s_cbranch_scc1 .LBB0_334
	s_mulk_i32 s3, 0x4200
	s_add_i32 s0, s3, 0
.Lconv_entry2:
	s_add_u32 s3, s58, 0x8f14000
	s_addc_u32 s8, s59, 0
	s_add_u32 s9, s58, 0x7f14000
	s_addc_u32 s10, s59, 0
	s_add_u32 s11, s58, 0x6f14000
	v_and_b32_e32 v4, 63, v254
	s_addc_u32 s14, s59, 0
	v_and_b32_e32 v0, 15, v254
	v_lshrrev_b32_e32 v3, 4, v4
	s_add_u32 s15, s58, 0x6d14000
	v_lshlrev_b32_e32 v30, 2, v0
	v_lshlrev_b32_e32 v0, 4, v0
	v_mul_u32_u24_e32 v2, 0x104, v3
	s_addc_u32 s36, s59, 0
	v_add3_u32 v5, s0, v0, v2
	v_lshlrev_b32_e32 v2, 3, v254
	s_add_u32 s37, s58, 0x6514000
	v_lshrrev_b32_e32 v4, 3, v4
	v_and_b32_e32 v2, 56, v2
	s_addc_u32 s38, s59, 0
	v_mov_b32_e32 v1, 0
	v_mul_u32_u24_e32 v6, 0x104, v2
	v_lshlrev_b32_e32 v8, 2, v4
	v_lshlrev_b32_e32 v4, 6, v4
	s_add_u32 s39, s58, 0xaf14000
	v_lshlrev_b32_e32 v31, 9, v3
	s_mov_b32 s1, 0
	v_add_u32_e32 v7, 0xc800, v5
	v_add3_u32 v9, s0, v6, v8
	v_or_b32_e32 v6, 0x200, v4
	v_or_b32_e32 v8, 0x400, v4
	v_or_b32_e32 v10, 0x600, v4
	v_or_b32_e32 v12, 0x800, v4
	v_or_b32_e32 v14, 0xa00, v4
	v_or_b32_e32 v16, 0xc00, v4
	v_or_b32_e32 v18, 0xe00, v4
	s_addc_u32 s41, s59, 0
	s_waitcnt lgkmcnt(0)
	v_lshl_add_u64 v[20:21], s[20:21], 0, v[0:1]
	v_lshl_add_u64 v[22:23], s[18:19], 0, v[0:1]
	v_lshl_add_u64 v[24:25], s[16:17], 0, v[0:1]
	v_lshl_add_u64 v[26:27], s[42:43], 0, v[0:1]
	v_lshl_add_u64 v[28:29], s[26:27], 0, v[0:1]
	s_lshl_b32 s16, s35, 6
	s_lshl_b32 s17, s40, 6
	s_lshl_b32 s18, s35, 4
	s_lshl_b32 s19, s40, 4
	s_lshl_b32 s20, s35, 12
	s_lshl_b32 s21, s40, 12
	s_lshl_b32 s26, s35, 3
	s_lshl_b32 s27, s40, 3
	v_add_u32_e32 v11, 0xc808, v5
	v_add_u32_e32 v13, 0xcc10, v5
	v_add_u32_e32 v15, 0xcc18, v5
	v_add_u32_e32 v17, 0xd020, v5
	v_add_u32_e32 v19, 0xd028, v5
	v_add_u32_e32 v32, 0xd430, v5
	v_add_u32_e32 v33, 0xd438, v5
	v_add_u32_e32 v34, 0xd840, v5
	s_movk_i32 s42, 0x6000
	v_lshlrev_b32_e32 v30, 2, v30
	v_lshlrev_b32_e32 v35, 2, v31
	s_movk_i32 s43, 0x2000
	s_movk_i32 s61, 0x4000
	s_mov_b32 s66, 0x8000
	s_mov_b32 s67, 0xa000
	s_mov_b32 s68, 0xc000
	s_mov_b32 s69, 0xe000
	s_mov_b32 s70, 0x10000
	s_mov_b32 s71, 0x12000
	s_mov_b32 s72, 0x14000
	s_mov_b32 s73, 0x16000
	s_mov_b32 s74, 0x18000
	s_mov_b32 s75, 0x1a000
	s_mov_b32 s76, 0x1c000
	s_mov_b32 s77, 0x1e000
	s_mov_b32 s78, 0x15800
	v_add_u32_e32 v36, 0xd848, v5
	v_add_u32_e32 v37, 0xdc50, v5
	v_add_u32_e32 v38, 0xdc58, v5
	v_add_u32_e32 v39, 0xe060, v5
	v_add_u32_e32 v40, 0xe068, v5
	v_add_u32_e32 v41, 0xe470, v5
	v_add_u32_e32 v42, 0xe478, v5
	v_add_u32_e32 v43, 0xe880, v5
	v_add_u32_e32 v44, 0xe888, v5
	v_add_u32_e32 v45, 0xec90, v5
	v_add_u32_e32 v46, 0xec98, v5
	s_branch .LBB0_314
.LBB0_313:
	s_add_i32 s35, s35, s40
	s_add_i32 s16, s16, s17
	s_add_i32 s18, s18, s19
	s_add_i32 s20, s20, s21
	s_add_i32 s26, s26, s27
	s_cmp_gt_i32 s35, s98
	s_cbranch_scc1 .LBB0_334

; __global__ void __launch_bounds__(NTHR, 2) mega_fwd(Params p) {
	.amdhsa_kernel _Z8mega_fwd6Params
		.amdhsa_group_segment_fixed_size 0
		.amdhsa_private_segment_fixed_size 0
		.amdhsa_kernarg_size 488
		.amdhsa_user_sgpr_count 2
		.amdhsa_user_sgpr_dispatch_ptr 0
		.amdhsa_user_sgpr_queue_ptr 0
		.amdhsa_user_sgpr_kernarg_segment_ptr 1
		.amdhsa_user_sgpr_dispatch_id 0
		.amdhsa_user_sgpr_kernarg_preload_length 0
		.amdhsa_user_sgpr_kernarg_preload_offset 0
		.amdhsa_user_sgpr_private_segment_size 0
		.amdhsa_uses_dynamic_stack 0
		.amdhsa_enable_private_segment 0
		.amdhsa_system_sgpr_workgroup_id_x 1
		.amdhsa_system_sgpr_workgroup_id_y 0
		.amdhsa_system_sgpr_workgroup_id_z 0
		.amdhsa_system_sgpr_workgroup_info 0
		.amdhsa_system_vgpr_workitem_id 2
		.amdhsa_next_free_vgpr 256
		.amdhsa_next_free_sgpr 100
		.amdhsa_accum_offset 256
		.amdhsa_reserve_vcc 1
		.amdhsa_float_round_mode_32 0
		.amdhsa_float_round_mode_16_64 0
		.amdhsa_float_denorm_mode_32 3
		.amdhsa_float_denorm_mode_16_64 3
		.amdhsa_dx10_clamp 1
		.amdhsa_ieee_mode 1
		.amdhsa_fp16_overflow 0
		.amdhsa_tg_split 0
		.amdhsa_exception_fp_ieee_invalid_op 0
		.amdhsa_exception_fp_denorm_src 0
		.amdhsa_exception_fp_ieee_div_zero 0
		.amdhsa_exception_fp_ieee_overflow 0
		.amdhsa_exception_fp_ieee_underflow 0
		.amdhsa_exception_fp_ieee_inexact 0
		.amdhsa_exception_int_div_zero 0
	.end_amdhsa_kernel

; __global__ void __launch_bounds__(NTHR, 2) mega_fwd(Params p) {
amdhsa.kernels:
  - .agpr_count:     0
    .args:
      - .offset:         0
        .size:           232
        .value_kind:     by_value
      - .offset:         232
        .size:           4
        .value_kind:     hidden_block_count_x
      - .offset:         236
        .size:           4
        .value_kind:     hidden_block_count_y
      - .offset:         240
        .size:           4
        .value_kind:     hidden_block_count_z
      - .offset:         244
        .size:           2
        .value_kind:     hidden_group_size_x
      - .offset:         246
        .size:           2
        .value_kind:     hidden_group_size_y
      - .offset:         248
        .size:           2
        .value_kind:     hidden_group_size_z
      - .offset:         250
        .size:           2
        .value_kind:     hidden_remainder_x
      - .offset:         252
        .size:           2
        .value_kind:     hidden_remainder_y
      - .offset:         254
        .size:           2
        .value_kind:     hidden_remainder_z
      - .offset:         272
        .size:           8
        .value_kind:     hidden_global_offset_x
      - .offset:         280
        .size:           8
        .value_kind:     hidden_global_offset_y
      - .offset:         288
        .size:           8
        .value_kind:     hidden_global_offset_z
      - .offset:         296
        .size:           2
        .value_kind:     hidden_grid_dims
      - .offset:         320
        .size:           8
        .value_kind:     hidden_multigrid_sync_arg
      - .offset:         352
        .size:           4
        .value_kind:     hidden_dynamic_lds_size
    .group_segment_fixed_size: 0
    .kernarg_segment_align: 8
    .kernarg_segment_size: 488
    .language:       OpenCL C
    .language_version:
      - 2
      - 0
    .max_flat_workgroup_size: 512
    .name:           _Z8mega_fwd6Params
    .private_segment_fixed_size: 0
    .sgpr_count:     106
    .sgpr_spill_count: 9
    .symbol:         _Z8mega_fwd6Params.kd
    .uniform_work_group_size: 1
    .uses_dynamic_stack: false
    .vgpr_count:     256
    .vgpr_spill_count: 0
    .wavefront_size: 64
